# stagger: half of the workgroups (bit 3 of block index) sleep about 1us before the GEMM2 prologue so sharers of a panel do not miss in lockstep
# speedup vs baseline: 1.0088x; 1.0088x over previous
.LBB0_808:
	v_mov_b32_e32 v14, v202
	s_waitcnt lgkmcnt(0)
	s_barrier
	s_bitcmp1_b32 s92, 3
	s_cbranch_scc0 .Lstag_skip
	s_sleep 32
.Lstag_skip:
	s_cmpk_gt_i32 s92, 0xff
	v_readfirstlane_b32 s13, v14
	s_cbranch_scc1 .LBB0_822
	s_ashr_i32 s0, s92, 31
	s_lshr_b32 s0, s0, 29
	s_add_i32 s8, s92, s0
	s_and_b32 s0, s8, -8
	s_sub_i32 s5, s92, s0
	s_cmp_gt_i32 s5, -1
	s_cbranch_scc0 .LBB0_811
	s_lshl_b32 s4, s5, 5
	s_cbranch_execz .LBB0_812
	s_branch .LBB0_813
